# E4/O5: blocks owning a small tile run it first (overlaps partner block's big tile)
# speedup vs baseline: 1.0058x; 1.0058x over previous
; DI int get_bid() { int b = blockIdx.x; asm volatile("" : "+s"(b)); return b; }
; DI void phase_even(const Params& p, int e, int sub, char* smem) {
;     ...
;     for (int t = get_bid(); t < 512 + 64; t += gridDim.x) {
;       if (t < 512) {
;         const int tm = t >> 3, tn = t & 7;
;         gemm_dma<256>(gbuf + (size_t)tm * 256 * 2048, 2048, W + WE_OUT + (size_t)tn * 128 * 2048, 2048, 2048, smem, tm * 256, tn * 128, epi);
;       } else {
;         const int u = t - 512, tm = u >> 3, tn = u & 7, m0 = M_PROMPT + tm * 64;
;         gemm_tile<2>(gbuf + (size_t)m0 * 2048, 2048, W + WE_OUT + (size_t)tn * 128 * 2048, 2048, 2048, smem, m0, tn * 128, epi);
.LBB0_21:
	s_andn2_b64 vcc, exec, s[38:39]
	s_cbranch_vccnz .LBB0_36
	s_mov_b32 s4, s2
	v_readlane_b32 s98, v255, 11
	s_nop 0
	s_cmp_lg_u32 s98, 0x200
	s_cbranch_scc1 .Lxmap_skip0
	s_cmp_lt_u32 s2, 64
	s_cbranch_scc0 .Lxmap_big0
	s_add_i32 s4, s2, 0x200
	s_branch .Lxmap_skip0
.Lxmap_big0:
	s_and_b32 s98, s2, 7
	s_lshl_b32 s98, s98, 6
	s_bfe_u32 s99, s2, 0x30006
	s_lshl_b32 s99, s99, 3
	s_or_b32 s98, s98, s99
	s_bfe_u32 s99, s2, 0x30003
	s_or_b32 s4, s98, s99

; DI int get_bid() { int b = blockIdx.x; asm volatile("" : "+s"(b)); return b; }
; DI void phase_even(const Params& p, int e, int sub, char* smem) {
;     ...
;     for (int t = get_bid(); t < 512 + 64; t += gridDim.x) {
;       if (t < 512) {
;         const int tm = t >> 3, tn = t & 7;
;         gemm_dma<256>(gbuf + (size_t)tm * 256 * 2048, 2048, W + WE_OUT + (size_t)tn * 128 * 2048, 2048, 2048, smem, tm * 256, tn * 128, epi);
;       } else {
;         const int u = t - 512, tm = u >> 3, tn = u & 7, m0 = M_PROMPT + tm * 64;
;         gemm_tile<2>(gbuf + (size_t)m0 * 2048, 2048, W + WE_OUT + (size_t)tn * 128 * 2048, 2048, 2048, smem, m0, tn * 128, epi);
.LBB0_25:
	v_readlane_b32 s8, v255, 5
	v_readlane_b32 s14, v255, 11
	v_readlane_b32 s7, v254, 56
	s_cmp_lg_u32 s14, 0x200
	s_cbranch_scc1 .Lxmap_lskip0
	s_cmpk_gt_i32 s6, 0x1ff
	s_cbranch_scc1 .Lxmap_lbig0
	s_movk_i32 s6, 0x400
	s_branch .Lxmap_lskip0
.Lxmap_lbig0:
	s_and_b32 s98, s2, 7
	s_lshl_b32 s98, s98, 6
	s_bfe_u32 s99, s2, 0x30006
	s_lshl_b32 s99, s99, 3
	s_or_b32 s98, s98, s99
	s_bfe_u32 s99, s2, 0x30003
	s_or_b32 s4, s98, s99
	s_sub_i32 s4, s4, 0x200
	s_mov_b32 s6, s4
	s_lshl_b32 s5, s4, 3

; DI int get_bid() { int b = blockIdx.x; asm volatile("" : "+s"(b)); return b; }
; DI void phase_even(const Params& p, int e, int sub, char* smem) {
;     ...
;     for (int t = get_bid(); t < 512 + 64; t += gridDim.x) {
;       if (t < 512) {
;         const int tm = t >> 3, tn = t & 7;
;         gemm_dma<256>(gbuf + (size_t)tm * 256 * 2048, 2048, W + WE_OUT + (size_t)tn * 128 * 2048, 2048, 2048, smem, tm * 256, tn * 128, epi);
;       } else {
;         const int u = t - 512, tm = u >> 3, tn = u & 7, m0 = M_PROMPT + tm * 64;
;         gemm_tile<2>(gbuf + (size_t)m0 * 2048, 2048, W + WE_OUT + (size_t)tn * 128 * 2048, 2048, 2048, smem, m0, tn * 128, epi);
.LBB0_282:
	s_and_b64 vcc, exec, s[38:39]
	s_cbranch_vccz .LBB0_294
	s_mov_b32 s4, s2
	v_readlane_b32 s98, v255, 11
	s_nop 0
	s_cmp_lg_u32 s98, 0x200
	s_cbranch_scc1 .Lxmap_skip2
	s_cmp_lt_u32 s2, 64
	s_cbranch_scc0 .Lxmap_big2
	s_add_i32 s4, s2, 0x200
	s_branch .Lxmap_skip2

; DI int get_bid() { int b = blockIdx.x; asm volatile("" : "+s"(b)); return b; }
; DI void phase_even(const Params& p, int e, int sub, char* smem) {
;     ...
;     for (int t = get_bid(); t < 512 + 64; t += gridDim.x) {
;       if (t < 512) {
;         const int tm = t >> 3, tn = t & 7;
;         gemm_dma<256>(gbuf + (size_t)tm * 256 * 2048, 2048, W + WE_OUT + (size_t)tn * 128 * 2048, 2048, 2048, smem, tm * 256, tn * 128, epi);
;       } else {
;         const int u = t - 512, tm = u >> 3, tn = u & 7, m0 = M_PROMPT + tm * 64;
;         gemm_tile<2>(gbuf + (size_t)m0 * 2048, 2048, W + WE_OUT + (size_t)tn * 128 * 2048, 2048, 2048, smem, m0, tn * 128, epi);
; DI void run_phase(const Params& p, int ph, char* smem) {
;   if (ph == 0) { convert_weights(p, 0, smem); prenorm0(p); }
;   else if (ph <= 5) phase_even(p, 0, ph - 1, smem);
.LBB0_1126:
	s_andn2_b64 vcc, exec, s[38:39]
	s_cbranch_vccnz .LBB0_1762
	v_readlane_b32 s4, v255, 27
	s_mov_b64 s[40:41], -1
	s_mov_b64 s[38:39], 0
	s_cmp_lt_i32 s4, 3
	s_mov_b64 s[82:83], 0
	s_cbranch_scc1 .LBB0_1160
	v_readlane_b32 s4, v255, 27
	s_cmp_gt_i32 s4, 3
	s_cbranch_scc0 .LBB0_1143
	s_cmp_eq_u32 s4, 4
	s_mov_b64 s[82:83], -1
	s_cbranch_scc0 .LBB0_1142
	s_mov_b32 s4, s2
	v_readlane_b32 s98, v255, 11
	s_nop 0
	s_cmp_lg_u32 s98, 0x200
	s_cbranch_scc1 .Lxmap_skip1
	s_cmp_lt_u32 s2, 64
	s_cbranch_scc0 .Lxmap_big1
	s_add_i32 s4, s2, 0x200
	s_branch .Lxmap_skip1

; DI int get_bid() { int b = blockIdx.x; asm volatile("" : "+s"(b)); return b; }
; DI void phase_even(const Params& p, int e, int sub, char* smem) {
;     ...
;     for (int t = get_bid(); t < 512 + 64; t += gridDim.x) {
;       if (t < 512) {
;         const int tm = t >> 3, tn = t & 7;
;         gemm_dma<256>(gbuf + (size_t)tm * 256 * 2048, 2048, W + WE_OUT + (size_t)tn * 128 * 2048, 2048, 2048, smem, tm * 256, tn * 128, epi);
;       } else {
;         const int u = t - 512, tm = u >> 3, tn = u & 7, m0 = M_PROMPT + tm * 64;
;         gemm_tile<2>(gbuf + (size_t)m0 * 2048, 2048, W + WE_OUT + (size_t)tn * 128 * 2048, 2048, 2048, smem, m0, tn * 128, epi);
.LBB0_1132:
	v_readlane_b32 s8, v255, 5
	v_readlane_b32 s14, v255, 11
	s_cmp_lg_u32 s14, 0x200
	s_cbranch_scc1 .Lxmap_lskip1
	s_cmpk_gt_i32 s6, 0x1ff
	s_cbranch_scc1 .Lxmap_lbig1
	s_movk_i32 s6, 0x400
	s_branch .Lxmap_lskip1
